# attention: no phi copies in tile2 tail, silu(z) loads one step early, MFMA->VALU distances fixed in row-max chains, padding nops removed
# speedup vs baseline: 1.0081x; 1.0081x over previous
; #define LAS __attribute__((address_space(3)))
; __device__ __forceinline__ float max3f(float a, float b, float c) { float r; asm("v_max3_f32 %0, %1, %2, %3" : "=v"(r) : "v"(a), "v"(b), "v"(c)); return r; }
; template <bool DIAG>
; __device__ __forceinline__ void attn_tile(LAS unsigned char* B, unsigned kf_off, unsigned vf_off, const bf16x8 (&qf)[4], f32x16& O0, f32x16& O1, float& mrun, float& lrun,
;                                           bool on, int kpos0, int qpos, int hh) {
;     constexpr int ROWB = 144;
;     const float cinit = on ? -mrun : -1e30f;
;     f32x16 st0, st1;
; #pragma unroll
;     for (int i = 0; i < 16; ++i) { st0[i] = cinit; st1[i] = cinit; }
; #pragma unroll
;     for (int s = 0; s < 4; ++s) {
;         const bf16x8 k0 = *(const LAS bf16x8*)(B + kf_off + s * 32), k1 = *(const LAS bf16x8*)(B + kf_off + 32 * ROWB + s * 32);
;         st0 = __builtin_amdgcn_mfma_f32_32x32x16_bf16(k0, qf[s], st0, 0, 0, 0);
;         st1 = __builtin_amdgcn_mfma_f32_32x32x16_bf16(k1, qf[s], st1, 0, 0, 0);
;     }
;     if (DIAG) {
; #pragma unroll
;         for (int i = 0; i < 16; ++i) {
;             const int key = kpos0 + (i & 7) + 8 * hh + 16 * (i >> 3);
;             if (key > qpos) st0[i] = -1e30f;
;             if (key + 32 > qpos) st1[i] = -1e30f;
;         }
;     }
;     float mx = max3f(st0[0], st0[1], st0[2]);
; #pragma unroll
;     for (int i = 3; i < 15; i += 2) mx = max3f(mx, st0[i], st0[i + 1]);
;     mx = max3f(mx, st0[15], st1[0]);
; #pragma unroll
;     for (int i = 1; i < 15; i += 2) mx = max3f(mx, st1[i], st1[i + 1]);
;     mx = fmaxf(mx, st1[15]);
;     if (__ballot(on && (mx > 8.f)) != 0ull) {
;         mx = fmaxf(mx, __shfl_xor(mx, 32));
;         const bool grow = on && (mx > 8.f);
;         const float d = grow ? mx : 0.f;
;         const float alpha = __builtin_amdgcn_exp2f(-d);
;         lrun *= alpha; mrun += d;
; #pragma unroll
;         for (int i = 0; i < 16; ++i) { O0[i] *= alpha; O1[i] *= alpha; st0[i] -= d; st1[i] -= d; }
;     }
.LBB0_385:
	s_bitcmp1_b32 s78, 0
	s_cselect_b32 s1, 0x9000, 0
	s_add_i32 s1, s1, 0
	s_cmp_gt_u32 s0, 3
	s_mov_b64 s[70:71], -1
	s_cbranch_scc1 .LBB0_390
	s_cmp_lg_u32 s3, s0
	s_cbranch_scc0 .LBB0_396
	v_mov_b64_e32 v[64:65], v[32:33]
	v_mov_b64_e32 v[80:81], v[48:49]
	s_cmp_ge_u32 s0, s3
	v_mov_b64_e32 v[62:63], v[30:31]
	v_mov_b64_e32 v[60:61], v[28:29]
	v_mov_b64_e32 v[58:59], v[26:27]
	v_mov_b64_e32 v[56:57], v[24:25]
	v_mov_b64_e32 v[54:55], v[22:23]
	v_mov_b64_e32 v[52:53], v[20:21]
	v_mov_b64_e32 v[50:51], v[18:19]
	v_mov_b64_e32 v[78:79], v[46:47]
	v_mov_b64_e32 v[76:77], v[44:45]
	v_mov_b64_e32 v[74:75], v[42:43]
	v_mov_b64_e32 v[72:73], v[40:41]
	v_mov_b64_e32 v[70:71], v[38:39]
	v_mov_b64_e32 v[68:69], v[36:37]
	v_mov_b64_e32 v[66:67], v[34:35]
	v_mov_b32_e32 v216, v214
	v_mov_b32_e32 v215, v2
	s_cbranch_scc1 .LBB0_403
	v_add_u32_e32 v12, s1, v197
	ds_read_b128 v[4:7], v12
	ds_read_b128 v[8:11], v12 offset:32
	v_xor_b32_e32 v82, 0x80000000, v2
	v_mov_b32_e32 v83, v82
	v_mov_b32_e32 v84, v82
	v_mov_b32_e32 v85, v82
	v_mov_b32_e32 v86, v82
	v_mov_b32_e32 v87, v82
	v_mov_b32_e32 v88, v82
	v_mov_b32_e32 v89, v82
	v_mov_b32_e32 v90, v82
	v_mov_b32_e32 v91, v82
	v_mov_b32_e32 v92, v82
	v_mov_b32_e32 v93, v82
	v_mov_b32_e32 v94, v82
	v_mov_b32_e32 v95, v82
	v_mov_b32_e32 v96, v82
	v_mov_b32_e32 v97, v82
	s_waitcnt lgkmcnt(1)
	s_nop 0
	v_mfma_f32_32x32x16_bf16 v[98:113], v[4:7], v[146:149], v[82:97]
	s_waitcnt lgkmcnt(0)
	v_mfma_f32_32x32x16_bf16 v[98:113], v[8:11], v[150:153], v[98:113]
	ds_read_b128 v[4:7], v12 offset:64
	ds_read_b128 v[8:11], v12 offset:96
	s_waitcnt lgkmcnt(1)
	v_mfma_f32_32x32x16_bf16 v[98:113], v[4:7], v[154:157], v[98:113]
	s_waitcnt lgkmcnt(0)
	v_mfma_f32_32x32x16_bf16 v[98:113], v[8:11], v[158:161], v[98:113]
	ds_read_b128 v[4:7], v12 offset:4608
	ds_read_b128 v[8:11], v12 offset:4640
	s_waitcnt lgkmcnt(1)
	v_mfma_f32_32x32x16_bf16 v[82:97], v[4:7], v[146:149], v[82:97]
	s_waitcnt lgkmcnt(0)
	v_mfma_f32_32x32x16_bf16 v[82:97], v[8:11], v[150:153], v[82:97]
	ds_read_b128 v[4:7], v12 offset:4672
	ds_read_b128 v[8:11], v12 offset:4704
	s_waitcnt lgkmcnt(1)
	v_mfma_f32_32x32x16_bf16 v[82:97], v[4:7], v[154:157], v[82:97]
	s_nop 1
	v_max3_f32 v4, v98, v99, v100
	s_nop 0
	v_max3_f32 v4, v4, v101, v102
	s_nop 0
	v_max3_f32 v4, v4, v103, v104
	s_nop 0
	v_max3_f32 v4, v4, v105, v106
	s_waitcnt lgkmcnt(0)
	v_mfma_f32_32x32x16_bf16 v[82:97], v[8:11], v[158:161], v[82:97]
	v_max3_f32 v4, v4, v107, v108
	s_nop 0
	v_max3_f32 v4, v4, v109, v110
	s_nop 0
	v_max3_f32 v4, v4, v111, v112
	s_nop 9
	v_max_f32_e32 v5, v97, v97
	v_max3_f32 v4, v4, v113, v82
	s_nop 0
	v_max3_f32 v4, v4, v83, v84
	s_nop 0
	v_max3_f32 v4, v4, v85, v86
	s_nop 0
	v_max3_f32 v4, v4, v87, v88
	s_nop 0
	v_max3_f32 v4, v4, v89, v90
	s_nop 0
	v_max3_f32 v4, v4, v91, v92
	s_nop 0
	v_max3_f32 v4, v4, v93, v94
	s_nop 0
	v_max3_f32 v4, v4, v95, v96
	s_nop 0
	v_max_f32_e32 v4, v4, v4
	v_max_f32_e32 v4, v4, v5
	v_cmp_lt_f32_e32 vcc, s91, v4
	s_cbranch_vccz .LBB0_401
	v_cmp_lt_i32_e32 vcc, v193, v202
	s_nop 1
	v_cndmask_b32_e32 v5, v192, v193, vcc
	v_lshlrev_b32_e32 v5, 2, v5
	ds_bpermute_b32 v5, v5, v4
	v_max_f32_e32 v4, v4, v4
	s_waitcnt lgkmcnt(0)
	v_max_f32_e32 v5, v5, v5
	v_max_f32_e32 v4, v4, v5
	v_cmp_lt_f32_e32 vcc, s91, v4
	s_nop 1
	v_cndmask_b32_e32 v6, 0, v4, vcc
	v_exp_f32_e64 v8, -v6
	v_add_f32_e32 v215, v2, v6
	v_pk_add_f32 v[98:99], v[98:99], v[6:7] op_sel_hi:[1,0] neg_lo:[0,1] neg_hi:[0,1]
	v_pk_add_f32 v[82:83], v[82:83], v[6:7] op_sel_hi:[1,0] neg_lo:[0,1] neg_hi:[0,1]
	v_pk_add_f32 v[100:101], v[100:101], v[6:7] op_sel_hi:[1,0] neg_lo:[0,1] neg_hi:[0,1]
	v_mul_f32_e32 v4, v214, v8
	v_pk_add_f32 v[84:85], v[84:85], v[6:7] op_sel_hi:[1,0] neg_lo:[0,1] neg_hi:[0,1]
	v_pk_add_f32 v[102:103], v[102:103], v[6:7] op_sel_hi:[1,0] neg_lo:[0,1] neg_hi:[0,1]
	v_pk_add_f32 v[86:87], v[86:87], v[6:7] op_sel_hi:[1,0] neg_lo:[0,1] neg_hi:[0,1]
	v_pk_add_f32 v[104:105], v[104:105], v[6:7] op_sel_hi:[1,0] neg_lo:[0,1] neg_hi:[0,1]
	v_pk_add_f32 v[88:89], v[88:89], v[6:7] op_sel_hi:[1,0] neg_lo:[0,1] neg_hi:[0,1]
	v_pk_add_f32 v[106:107], v[106:107], v[6:7] op_sel_hi:[1,0] neg_lo:[0,1] neg_hi:[0,1]
	v_pk_add_f32 v[90:91], v[90:91], v[6:7] op_sel_hi:[1,0] neg_lo:[0,1] neg_hi:[0,1]
	v_pk_add_f32 v[108:109], v[108:109], v[6:7] op_sel_hi:[1,0] neg_lo:[0,1] neg_hi:[0,1]
	v_pk_add_f32 v[92:93], v[92:93], v[6:7] op_sel_hi:[1,0] neg_lo:[0,1] neg_hi:[0,1]
	v_pk_add_f32 v[110:111], v[110:111], v[6:7] op_sel_hi:[1,0] neg_lo:[0,1] neg_hi:[0,1]
	v_pk_add_f32 v[94:95], v[94:95], v[6:7] op_sel_hi:[1,0] neg_lo:[0,1] neg_hi:[0,1]
	v_pk_mul_f32 v[64:65], v[32:33], v[8:9] op_sel_hi:[1,0]
	v_pk_mul_f32 v[62:63], v[30:31], v[8:9] op_sel_hi:[1,0]
	v_pk_mul_f32 v[60:61], v[28:29], v[8:9] op_sel_hi:[1,0]
	v_pk_mul_f32 v[58:59], v[26:27], v[8:9] op_sel_hi:[1,0]
	v_pk_mul_f32 v[56:57], v[24:25], v[8:9] op_sel_hi:[1,0]
	v_pk_mul_f32 v[54:55], v[22:23], v[8:9] op_sel_hi:[1,0]
	v_pk_mul_f32 v[52:53], v[20:21], v[8:9] op_sel_hi:[1,0]
	v_pk_mul_f32 v[50:51], v[18:19], v[8:9] op_sel_hi:[1,0]
	v_pk_mul_f32 v[80:81], v[48:49], v[8:9] op_sel_hi:[1,0]
	v_pk_mul_f32 v[78:79], v[46:47], v[8:9] op_sel_hi:[1,0]
	v_pk_mul_f32 v[76:77], v[44:45], v[8:9] op_sel_hi:[1,0]
	v_pk_mul_f32 v[74:75], v[42:43], v[8:9] op_sel_hi:[1,0]
	v_pk_mul_f32 v[72:73], v[40:41], v[8:9] op_sel_hi:[1,0]
	v_pk_mul_f32 v[70:71], v[38:39], v[8:9] op_sel_hi:[1,0]
	v_pk_mul_f32 v[68:69], v[36:37], v[8:9] op_sel_hi:[1,0]
	v_pk_mul_f32 v[66:67], v[34:35], v[8:9] op_sel_hi:[1,0]
	v_pk_add_f32 v[112:113], v[112:113], v[6:7] op_sel_hi:[1,0] neg_lo:[0,1] neg_hi:[0,1]
	v_pk_add_f32 v[96:97], v[96:97], v[6:7] op_sel_hi:[1,0] neg_lo:[0,1] neg_hi:[0,1]
	s_branch .LBB0_402
; #define LAS __attribute__((address_space(3)))
; __device__ __forceinline__ float max3f(float a, float b, float c) { float r; asm("v_max3_f32 %0, %1, %2, %3" : "=v"(r) : "v"(a), "v"(b), "v"(c)); return r; }
; __device__ __forceinline__ void attn_tile2(LAS unsigned char* BA, LAS unsigned char* BB, unsigned kf_off, unsigned vf_off, const bf16x8 (&qf)[4], f32x16& O0, f32x16& O1, float& mrun, float& lrun, bool on) {
;     constexpr int ROWB = 144;
;     const float cinit = on ? -mrun : -1e30f;
;     f32x16 sa0, sa1, sb0, sb1;
; #pragma unroll
;     for (int i = 0; i < 16; ++i) { sa0[i] = cinit; sa1[i] = cinit; sb0[i] = cinit; sb1[i] = cinit; }
; #pragma unroll
;     for (int s = 0; s < 4; ++s) {
;         const bf16x8 k0 = *(const LAS bf16x8*)(BA + kf_off + s * 32), k1 = *(const LAS bf16x8*)(BA + kf_off + 32 * ROWB + s * 32);
;         const bf16x8 k2 = *(const LAS bf16x8*)(BB + kf_off + s * 32), k3 = *(const LAS bf16x8*)(BB + kf_off + 32 * ROWB + s * 32);
;         sa0 = __builtin_amdgcn_mfma_f32_32x32x16_bf16(k0, qf[s], sa0, 0, 0, 0);
;         sa1 = __builtin_amdgcn_mfma_f32_32x32x16_bf16(k1, qf[s], sa1, 0, 0, 0);
;         sb0 = __builtin_amdgcn_mfma_f32_32x32x16_bf16(k2, qf[s], sb0, 0, 0, 0);
;         sb1 = __builtin_amdgcn_mfma_f32_32x32x16_bf16(k3, qf[s], sb1, 0, 0, 0);
;     }
;     float mx = max3f(sa0[0], sa0[1], sa0[2]), my = max3f(sb0[0], sb0[1], sb0[2]);
; #pragma unroll
;     for (int i = 3; i < 15; i += 2) { mx = max3f(mx, sa0[i], sa0[i + 1]); my = max3f(my, sb0[i], sb0[i + 1]); }
;     mx = max3f(mx, sa0[15], sa1[0]); my = max3f(my, sb0[15], sb1[0]);
; #pragma unroll
;     for (int i = 1; i < 15; i += 2) { mx = max3f(mx, sa1[i], sa1[i + 1]); my = max3f(my, sb1[i], sb1[i + 1]); }
;     mx = max3f(mx, sa1[15], fmaxf(my, sb1[15]));
;     if (__ballot(on && (mx > 8.f)) != 0ull) {
.LBB0_390:
	s_and_b64 vcc, exec, s[70:71]
	s_cbranch_vccz .LBB0_416
	s_add_i32 s0, s0, -4
	s_lshr_b32 s0, s0, 2
	v_lshrrev_b32_e32 v4, s0, v213
	v_and_b32_e32 v4, 1, v4
	v_cmp_eq_u32_e64 s[70:71], 1, v4
	v_bfe_u32 v4, v213, s0, 1
	v_cmp_ne_u32_e32 vcc, 0, v4
	s_cbranch_vccz .LBB0_395
	v_add_u32_e32 v16, s1, v197
	ds_read_b128 v[4:7], v16
	ds_read_b128 v[8:11], v16 offset:32
	v_cndmask_b32_e64 v50, v211, -v2, s[70:71]
	v_mov_b32_e32 v51, v50
	v_mov_b32_e32 v52, v50
	v_mov_b32_e32 v53, v50
	v_mov_b32_e32 v54, v50
	v_mov_b32_e32 v55, v50
	v_mov_b32_e32 v56, v50
	v_mov_b32_e32 v57, v50
	v_mov_b32_e32 v58, v50
	v_mov_b32_e32 v59, v50
	v_mov_b32_e32 v60, v50
	v_mov_b32_e32 v61, v50
	v_mov_b32_e32 v62, v50
	v_mov_b32_e32 v63, v50
	v_mov_b32_e32 v64, v50
	v_mov_b32_e32 v65, v50
	s_waitcnt lgkmcnt(1)
	s_nop 0
	v_mfma_f32_32x32x16_bf16 v[82:97], v[4:7], v[146:149], v[50:65]
	ds_read_b128 v[4:7], v16 offset:18432
	ds_read_b128 v[12:15], v16 offset:18464
	s_waitcnt lgkmcnt(1)
	v_mfma_f32_32x32x16_bf16 v[66:81], v[4:7], v[146:149], v[50:65]
	v_mfma_f32_32x32x16_bf16 v[82:97], v[8:11], v[150:153], v[82:97]
	ds_read_b128 v[4:7], v16 offset:64
	ds_read_b128 v[8:11], v16 offset:96
	s_waitcnt lgkmcnt(2)
	v_mfma_f32_32x32x16_bf16 v[66:81], v[12:15], v[150:153], v[66:81]
	s_waitcnt lgkmcnt(1)
	v_mfma_f32_32x32x16_bf16 v[82:97], v[4:7], v[154:157], v[82:97]
	ds_read_b128 v[4:7], v16 offset:18496
	ds_read_b128 v[12:15], v16 offset:18528
	s_waitcnt lgkmcnt(1)
	v_mfma_f32_32x32x16_bf16 v[66:81], v[4:7], v[154:157], v[66:81]
	v_mfma_f32_32x32x16_bf16 v[82:97], v[8:11], v[158:161], v[82:97]
	ds_read_b128 v[4:7], v16 offset:4608
	ds_read_b128 v[8:11], v16 offset:4640
	s_waitcnt lgkmcnt(2)
	v_mfma_f32_32x32x16_bf16 v[66:81], v[12:15], v[158:161], v[66:81]
	s_waitcnt lgkmcnt(1)
	v_mfma_f32_32x32x16_bf16 v[98:113], v[4:7], v[146:149], v[50:65]
	ds_read_b128 v[4:7], v16 offset:23040
	ds_read_b128 v[12:15], v16 offset:23072
	s_waitcnt lgkmcnt(1)
	v_mfma_f32_32x32x16_bf16 v[50:65], v[4:7], v[146:149], v[50:65]
	v_mfma_f32_32x32x16_bf16 v[98:113], v[8:11], v[150:153], v[98:113]
	ds_read_b128 v[4:7], v16 offset:4672
	ds_read_b128 v[8:11], v16 offset:4704
	s_waitcnt lgkmcnt(2)
	v_mfma_f32_32x32x16_bf16 v[50:65], v[12:15], v[150:153], v[50:65]
	s_waitcnt lgkmcnt(1)
	v_mfma_f32_32x32x16_bf16 v[98:113], v[4:7], v[154:157], v[98:113]
	ds_read_b128 v[4:7], v16 offset:23104
	ds_read_b128 v[12:15], v16 offset:23136
	v_max3_f32 v16, v82, v83, v84
	s_waitcnt lgkmcnt(1)
	v_mfma_f32_32x32x16_bf16 v[50:65], v[4:7], v[154:157], v[50:65]
	v_max3_f32 v4, v66, v67, v68
	v_max3_f32 v5, v16, v85, v86
	v_max3_f32 v4, v4, v69, v70
	v_max3_f32 v5, v5, v87, v88
	v_max3_f32 v4, v4, v71, v72
	v_max3_f32 v5, v5, v89, v90
	s_waitcnt lgkmcnt(0)
	v_mfma_f32_32x32x16_bf16 v[50:65], v[12:15], v[158:161], v[50:65]
	v_mfma_f32_32x32x16_bf16 v[98:113], v[8:11], v[158:161], v[98:113]
	v_max3_f32 v4, v4, v73, v74
	v_max3_f32 v5, v5, v91, v92
	v_max3_f32 v4, v4, v75, v76
	v_max3_f32 v5, v5, v93, v94
	v_max3_f32 v4, v4, v77, v78
	v_max3_f32 v5, v5, v95, v96
	v_max3_f32 v4, v4, v79, v80
	s_nop 4
	v_max_f32_e32 v6, v65, v65
	v_max3_f32 v5, v5, v97, v98
	v_max3_f32 v4, v4, v81, v50
	v_max3_f32 v5, v5, v99, v100
	v_max3_f32 v4, v4, v51, v52
	v_max3_f32 v5, v5, v101, v102
	v_max3_f32 v4, v4, v53, v54
	v_max3_f32 v5, v5, v103, v104
	v_max3_f32 v4, v4, v55, v56
	v_max3_f32 v5, v5, v105, v106
	v_max3_f32 v4, v4, v57, v58
	v_max3_f32 v5, v5, v107, v108
	v_max3_f32 v4, v4, v59, v60
	v_max3_f32 v5, v5, v109, v110
	v_max3_f32 v4, v4, v61, v62
	v_max3_f32 v5, v5, v111, v112
	v_max3_f32 v4, v4, v63, v64
	v_max_f32_e32 v4, v4, v4
	v_max_f32_e32 v4, v4, v6
	v_max3_f32 v4, v5, v113, v4
	v_cmp_lt_f32_e32 vcc, s91, v4
	s_and_b64 vcc, s[70:71], vcc
	s_cbranch_vccz .LBB0_394
; __device__ __forceinline__ void attn_tile2(LAS unsigned char* BA, LAS unsigned char* BB, unsigned kf_off, unsigned vf_off, const bf16x8 (&qf)[4], f32x16& O0, f32x16& O1, float& mrun, float& lrun, bool on) {
;     ...
;     if (__ballot(on && (mx > 8.f)) != 0ull) {
;         mx = fmaxf(mx, __shfl_xor(mx, 32));
;         const bool grow = on && (mx > 8.f);
;         const float d = grow ? mx : 0.f;
;         const float alpha = __builtin_amdgcn_exp2f(-d);
;         lrun *= alpha; mrun += d;
; #pragma unroll
;         for (int i = 0; i < 16; ++i) { O0[i] *= alpha; O1[i] *= alpha; sa0[i] -= d; sa1[i] -= d; sb0[i] -= d; sb1[i] -= d; }
;     }
	v_cmp_lt_i32_e32 vcc, v193, v202
	s_nop 1
	v_cndmask_b32_e32 v5, v192, v193, vcc
	v_lshlrev_b32_e32 v5, 2, v5
	ds_bpermute_b32 v5, v5, v4
	v_max_f32_e32 v4, v4, v4
	s_waitcnt lgkmcnt(0)
	v_max_f32_e32 v5, v5, v5
	v_max_f32_e32 v4, v4, v5
	v_cmp_lt_f32_e32 vcc, s91, v4
	s_and_b64 vcc, s[70:71], vcc
	s_nop 0
	v_cndmask_b32_e32 v4, 0, v4, vcc
	v_exp_f32_e64 v6, -v4
	v_add_f32_e32 v2, v2, v4
	v_pk_add_f32 v[82:83], v[82:83], v[4:5] op_sel_hi:[1,0] neg_lo:[0,1] neg_hi:[0,1]
	v_pk_add_f32 v[98:99], v[98:99], v[4:5] op_sel_hi:[1,0] neg_lo:[0,1] neg_hi:[0,1]
	v_pk_add_f32 v[66:67], v[66:67], v[4:5] op_sel_hi:[1,0] neg_lo:[0,1] neg_hi:[0,1]
	v_mul_f32_e32 v214, v214, v6
	v_pk_add_f32 v[50:51], v[50:51], v[4:5] op_sel_hi:[1,0] neg_lo:[0,1] neg_hi:[0,1]
	v_pk_add_f32 v[84:85], v[84:85], v[4:5] op_sel_hi:[1,0] neg_lo:[0,1] neg_hi:[0,1]
	v_pk_add_f32 v[100:101], v[100:101], v[4:5] op_sel_hi:[1,0] neg_lo:[0,1] neg_hi:[0,1]
	v_pk_add_f32 v[68:69], v[68:69], v[4:5] op_sel_hi:[1,0] neg_lo:[0,1] neg_hi:[0,1]
	v_pk_add_f32 v[52:53], v[52:53], v[4:5] op_sel_hi:[1,0] neg_lo:[0,1] neg_hi:[0,1]
	v_pk_add_f32 v[86:87], v[86:87], v[4:5] op_sel_hi:[1,0] neg_lo:[0,1] neg_hi:[0,1]
	v_pk_add_f32 v[102:103], v[102:103], v[4:5] op_sel_hi:[1,0] neg_lo:[0,1] neg_hi:[0,1]
	v_pk_add_f32 v[70:71], v[70:71], v[4:5] op_sel_hi:[1,0] neg_lo:[0,1] neg_hi:[0,1]
	v_pk_add_f32 v[54:55], v[54:55], v[4:5] op_sel_hi:[1,0] neg_lo:[0,1] neg_hi:[0,1]
	v_pk_add_f32 v[88:89], v[88:89], v[4:5] op_sel_hi:[1,0] neg_lo:[0,1] neg_hi:[0,1]
	v_pk_add_f32 v[104:105], v[104:105], v[4:5] op_sel_hi:[1,0] neg_lo:[0,1] neg_hi:[0,1]
	v_pk_add_f32 v[72:73], v[72:73], v[4:5] op_sel_hi:[1,0] neg_lo:[0,1] neg_hi:[0,1]
	v_pk_add_f32 v[56:57], v[56:57], v[4:5] op_sel_hi:[1,0] neg_lo:[0,1] neg_hi:[0,1]
	v_pk_add_f32 v[90:91], v[90:91], v[4:5] op_sel_hi:[1,0] neg_lo:[0,1] neg_hi:[0,1]
	v_pk_add_f32 v[106:107], v[106:107], v[4:5] op_sel_hi:[1,0] neg_lo:[0,1] neg_hi:[0,1]
	v_pk_add_f32 v[74:75], v[74:75], v[4:5] op_sel_hi:[1,0] neg_lo:[0,1] neg_hi:[0,1]
	v_pk_add_f32 v[58:59], v[58:59], v[4:5] op_sel_hi:[1,0] neg_lo:[0,1] neg_hi:[0,1]
	v_pk_add_f32 v[92:93], v[92:93], v[4:5] op_sel_hi:[1,0] neg_lo:[0,1] neg_hi:[0,1]
	v_pk_add_f32 v[108:109], v[108:109], v[4:5] op_sel_hi:[1,0] neg_lo:[0,1] neg_hi:[0,1]
	v_pk_add_f32 v[76:77], v[76:77], v[4:5] op_sel_hi:[1,0] neg_lo:[0,1] neg_hi:[0,1]
	v_pk_add_f32 v[60:61], v[60:61], v[4:5] op_sel_hi:[1,0] neg_lo:[0,1] neg_hi:[0,1]
	v_pk_add_f32 v[94:95], v[94:95], v[4:5] op_sel_hi:[1,0] neg_lo:[0,1] neg_hi:[0,1]
	v_pk_add_f32 v[110:111], v[110:111], v[4:5] op_sel_hi:[1,0] neg_lo:[0,1] neg_hi:[0,1]
	v_pk_add_f32 v[78:79], v[78:79], v[4:5] op_sel_hi:[1,0] neg_lo:[0,1] neg_hi:[0,1]
	v_pk_add_f32 v[62:63], v[62:63], v[4:5] op_sel_hi:[1,0] neg_lo:[0,1] neg_hi:[0,1]
	v_pk_mul_f32 v[32:33], v[32:33], v[6:7] op_sel_hi:[1,0]
	v_pk_mul_f32 v[30:31], v[30:31], v[6:7] op_sel_hi:[1,0]
	v_pk_mul_f32 v[28:29], v[28:29], v[6:7] op_sel_hi:[1,0]
	v_pk_mul_f32 v[26:27], v[26:27], v[6:7] op_sel_hi:[1,0]
	v_pk_mul_f32 v[24:25], v[24:25], v[6:7] op_sel_hi:[1,0]
	v_pk_mul_f32 v[22:23], v[22:23], v[6:7] op_sel_hi:[1,0]
	v_pk_mul_f32 v[20:21], v[20:21], v[6:7] op_sel_hi:[1,0]
	v_pk_mul_f32 v[18:19], v[18:19], v[6:7] op_sel_hi:[1,0]
	v_pk_mul_f32 v[48:49], v[48:49], v[6:7] op_sel_hi:[1,0]
	v_pk_mul_f32 v[46:47], v[46:47], v[6:7] op_sel_hi:[1,0]
	v_pk_mul_f32 v[44:45], v[44:45], v[6:7] op_sel_hi:[1,0]
	v_pk_mul_f32 v[42:43], v[42:43], v[6:7] op_sel_hi:[1,0]
	v_pk_mul_f32 v[40:41], v[40:41], v[6:7] op_sel_hi:[1,0]
	v_pk_mul_f32 v[38:39], v[38:39], v[6:7] op_sel_hi:[1,0]
	v_pk_mul_f32 v[36:37], v[36:37], v[6:7] op_sel_hi:[1,0]
	v_pk_mul_f32 v[34:35], v[34:35], v[6:7] op_sel_hi:[1,0]
	v_pk_add_f32 v[96:97], v[96:97], v[4:5] op_sel_hi:[1,0] neg_lo:[0,1] neg_hi:[0,1]
	v_pk_add_f32 v[112:113], v[112:113], v[4:5] op_sel_hi:[1,0] neg_lo:[0,1] neg_hi:[0,1]
	v_pk_add_f32 v[80:81], v[80:81], v[4:5] op_sel_hi:[1,0] neg_lo:[0,1] neg_hi:[0,1]
	v_pk_add_f32 v[64:65], v[64:65], v[4:5] op_sel_hi:[1,0] neg_lo:[0,1] neg_hi:[0,1]

; #define LAS __attribute__((address_space(3)))
; __device__ __forceinline__ float max3f(float a, float b, float c) { float r; asm("v_max3_f32 %0, %1, %2, %3" : "=v"(r) : "v"(a), "v"(b), "v"(c)); return r; }
; template <bool DIAG>
; __device__ __forceinline__ void attn_tile(LAS unsigned char* B, unsigned kf_off, unsigned vf_off, const bf16x8 (&qf)[4], f32x16& O0, f32x16& O1, float& mrun, float& lrun,
;                                           bool on, int kpos0, int qpos, int hh) {
;     constexpr int ROWB = 144;
;     const float cinit = on ? -mrun : -1e30f;
;     f32x16 st0, st1;
; #pragma unroll
;     for (int i = 0; i < 16; ++i) { st0[i] = cinit; st1[i] = cinit; }
; #pragma unroll
;     for (int s = 0; s < 4; ++s) {
;         const bf16x8 k0 = *(const LAS bf16x8*)(B + kf_off + s * 32), k1 = *(const LAS bf16x8*)(B + kf_off + 32 * ROWB + s * 32);
;         st0 = __builtin_amdgcn_mfma_f32_32x32x16_bf16(k0, qf[s], st0, 0, 0, 0);
;         st1 = __builtin_amdgcn_mfma_f32_32x32x16_bf16(k1, qf[s], st1, 0, 0, 0);
;     }
;     if (DIAG) {
; #pragma unroll
;         for (int i = 0; i < 16; ++i) {
;             const int key = kpos0 + (i & 7) + 8 * hh + 16 * (i >> 3);
;             if (key > qpos) st0[i] = -1e30f;
;             if (key + 32 > qpos) st1[i] = -1e30f;
;         }
;     }
;     float mx = max3f(st0[0], st0[1], st0[2]);
; #pragma unroll
;     for (int i = 3; i < 15; i += 2) mx = max3f(mx, st0[i], st0[i + 1]);
;     mx = max3f(mx, st0[15], st1[0]);
; #pragma unroll
;     for (int i = 1; i < 15; i += 2) mx = max3f(mx, st1[i], st1[i + 1]);
;     mx = fmaxf(mx, st1[15]);
;     if (__ballot(on && (mx > 8.f)) != 0ull) {
;         mx = fmaxf(mx, __shfl_xor(mx, 32));
;         const bool grow = on && (mx > 8.f);
;         const float d = grow ? mx : 0.f;
;         const float alpha = __builtin_amdgcn_exp2f(-d);
;         lrun *= alpha; mrun += d;
; #pragma unroll
;         for (int i = 0; i < 16; ++i) { O0[i] *= alpha; O1[i] *= alpha; st0[i] -= d; st1[i] -= d; }
;     }
.LBB0_398:
	s_add_i32 s70, s0, 1
	s_nop 4
	v_mov_b64_e32 v[112:113], v[64:65]
	s_nop 1
	v_mov_b64_e32 v[96:97], v[80:81]
	s_cmp_ge_u32 s70, s3
	v_mov_b64_e32 v[110:111], v[62:63]
	v_mov_b64_e32 v[108:109], v[60:61]
	v_mov_b64_e32 v[106:107], v[58:59]
	v_mov_b64_e32 v[104:105], v[56:57]
	v_mov_b64_e32 v[102:103], v[54:55]
	v_mov_b64_e32 v[100:101], v[52:53]
	v_mov_b64_e32 v[98:99], v[50:51]
	v_mov_b64_e32 v[94:95], v[78:79]
	v_mov_b64_e32 v[92:93], v[76:77]
	v_mov_b64_e32 v[90:91], v[74:75]
	v_mov_b64_e32 v[88:89], v[72:73]
	v_mov_b64_e32 v[86:87], v[70:71]
	v_mov_b64_e32 v[84:85], v[68:69]
	v_mov_b64_e32 v[82:83], v[66:67]
	v_mov_b32_e32 v5, v216
	v_mov_b32_e32 v4, v215
	s_cbranch_scc1 .LBB0_414
	v_add_u32_e32 v12, s1, v197
	ds_read_b128 v[4:7], v12 offset:18432
	ds_read_b128 v[8:11], v12 offset:18464
	v_xor_b32_e32 v114, 0x80000000, v215
	v_mov_b32_e32 v115, v114
	v_mov_b32_e32 v116, v114
	v_mov_b32_e32 v117, v114
	v_mov_b32_e32 v118, v114
	v_mov_b32_e32 v119, v114
	v_mov_b32_e32 v120, v114
	v_mov_b32_e32 v121, v114
	v_mov_b32_e32 v122, v114
	v_mov_b32_e32 v123, v114
	v_mov_b32_e32 v124, v114
	v_mov_b32_e32 v125, v114
	v_mov_b32_e32 v126, v114
	v_mov_b32_e32 v127, v114
	v_mov_b32_e32 v128, v114
	v_mov_b32_e32 v129, v114
	s_waitcnt lgkmcnt(1)
	s_nop 0
	v_mfma_f32_32x32x16_bf16 v[130:145], v[4:7], v[146:149], v[114:129]
	s_waitcnt lgkmcnt(0)
	v_mfma_f32_32x32x16_bf16 v[130:145], v[8:11], v[150:153], v[130:145]
	ds_read_b128 v[4:7], v12 offset:18496
	ds_read_b128 v[8:11], v12 offset:18528
	s_waitcnt lgkmcnt(1)
	v_mfma_f32_32x32x16_bf16 v[130:145], v[4:7], v[154:157], v[130:145]
	s_waitcnt lgkmcnt(0)
	v_mfma_f32_32x32x16_bf16 v[130:145], v[8:11], v[158:161], v[130:145]
	ds_read_b128 v[4:7], v12 offset:23040
	ds_read_b128 v[8:11], v12 offset:23072
	s_waitcnt lgkmcnt(1)
	v_mfma_f32_32x32x16_bf16 v[114:129], v[4:7], v[146:149], v[114:129]
	s_waitcnt lgkmcnt(0)
	v_mfma_f32_32x32x16_bf16 v[114:129], v[8:11], v[150:153], v[114:129]
	ds_read_b128 v[4:7], v12 offset:23104
	ds_read_b128 v[8:11], v12 offset:23136
	s_waitcnt lgkmcnt(1)
	v_mfma_f32_32x32x16_bf16 v[114:129], v[4:7], v[154:157], v[114:129]
	s_nop 1
	v_max3_f32 v4, v130, v131, v132
	s_nop 0
	v_max3_f32 v4, v4, v133, v134
	s_nop 0
	v_max3_f32 v4, v4, v135, v136
	s_nop 0
	v_max3_f32 v4, v4, v137, v138
	s_waitcnt lgkmcnt(0)
	v_mfma_f32_32x32x16_bf16 v[114:129], v[8:11], v[158:161], v[114:129]
	v_max3_f32 v4, v4, v139, v140
	s_nop 0
	v_max3_f32 v4, v4, v141, v142
	s_nop 0
	v_max3_f32 v4, v4, v143, v144
	s_nop 9
	v_max_f32_e32 v5, v129, v129
	v_max3_f32 v4, v4, v145, v114
	s_nop 0
	v_max3_f32 v4, v4, v115, v116
	s_nop 0
	v_max3_f32 v4, v4, v117, v118
	s_nop 0
	v_max3_f32 v4, v4, v119, v120
	s_nop 0
	v_max3_f32 v4, v4, v121, v122
	s_nop 0
	v_max3_f32 v4, v4, v123, v124
	s_nop 0
	v_max3_f32 v4, v4, v125, v126
	s_nop 0
	v_max3_f32 v4, v4, v127, v128
	s_nop 0
	v_max_f32_e32 v4, v4, v4
	v_max_f32_e32 v4, v4, v5
	v_cmp_lt_f32_e32 vcc, s91, v4
	s_cbranch_vccz .LBB0_412
	v_cmp_lt_i32_e32 vcc, v193, v202
	s_nop 1
	v_cndmask_b32_e32 v5, v192, v193, vcc
	v_lshlrev_b32_e32 v5, 2, v5
	ds_bpermute_b32 v5, v5, v4
	v_max_f32_e32 v4, v4, v4
	s_waitcnt lgkmcnt(0)
	v_max_f32_e32 v5, v5, v5
	v_max_f32_e32 v4, v4, v5
	v_cmp_lt_f32_e32 vcc, s91, v4
	s_nop 1
	v_cndmask_b32_e32 v6, 0, v4, vcc
	v_exp_f32_e64 v8, -v6
	v_add_f32_e32 v4, v215, v6
	v_pk_add_f32 v[130:131], v[130:131], v[6:7] op_sel_hi:[1,0] neg_lo:[0,1] neg_hi:[0,1]
	v_pk_add_f32 v[114:115], v[114:115], v[6:7] op_sel_hi:[1,0] neg_lo:[0,1] neg_hi:[0,1]
	v_pk_add_f32 v[132:133], v[132:133], v[6:7] op_sel_hi:[1,0] neg_lo:[0,1] neg_hi:[0,1]
	v_mul_f32_e32 v5, v216, v8
	v_pk_add_f32 v[116:117], v[116:117], v[6:7] op_sel_hi:[1,0] neg_lo:[0,1] neg_hi:[0,1]
	v_pk_add_f32 v[134:135], v[134:135], v[6:7] op_sel_hi:[1,0] neg_lo:[0,1] neg_hi:[0,1]
	v_pk_add_f32 v[118:119], v[118:119], v[6:7] op_sel_hi:[1,0] neg_lo:[0,1] neg_hi:[0,1]
	v_pk_add_f32 v[136:137], v[136:137], v[6:7] op_sel_hi:[1,0] neg_lo:[0,1] neg_hi:[0,1]
	v_pk_add_f32 v[120:121], v[120:121], v[6:7] op_sel_hi:[1,0] neg_lo:[0,1] neg_hi:[0,1]
	v_pk_add_f32 v[138:139], v[138:139], v[6:7] op_sel_hi:[1,0] neg_lo:[0,1] neg_hi:[0,1]
	v_pk_add_f32 v[122:123], v[122:123], v[6:7] op_sel_hi:[1,0] neg_lo:[0,1] neg_hi:[0,1]
	v_pk_add_f32 v[140:141], v[140:141], v[6:7] op_sel_hi:[1,0] neg_lo:[0,1] neg_hi:[0,1]
	v_pk_add_f32 v[124:125], v[124:125], v[6:7] op_sel_hi:[1,0] neg_lo:[0,1] neg_hi:[0,1]
	v_pk_add_f32 v[142:143], v[142:143], v[6:7] op_sel_hi:[1,0] neg_lo:[0,1] neg_hi:[0,1]
	v_pk_add_f32 v[126:127], v[126:127], v[6:7] op_sel_hi:[1,0] neg_lo:[0,1] neg_hi:[0,1]
	v_pk_mul_f32 v[112:113], v[64:65], v[8:9] op_sel_hi:[1,0]
	v_pk_mul_f32 v[110:111], v[62:63], v[8:9] op_sel_hi:[1,0]
	v_pk_mul_f32 v[108:109], v[60:61], v[8:9] op_sel_hi:[1,0]
	v_pk_mul_f32 v[106:107], v[58:59], v[8:9] op_sel_hi:[1,0]
	v_pk_mul_f32 v[104:105], v[56:57], v[8:9] op_sel_hi:[1,0]
	v_pk_mul_f32 v[102:103], v[54:55], v[8:9] op_sel_hi:[1,0]
	v_pk_mul_f32 v[100:101], v[52:53], v[8:9] op_sel_hi:[1,0]
	v_pk_mul_f32 v[98:99], v[50:51], v[8:9] op_sel_hi:[1,0]
	v_pk_mul_f32 v[96:97], v[80:81], v[8:9] op_sel_hi:[1,0]
	v_pk_mul_f32 v[94:95], v[78:79], v[8:9] op_sel_hi:[1,0]
	v_pk_mul_f32 v[92:93], v[76:77], v[8:9] op_sel_hi:[1,0]
	v_pk_mul_f32 v[90:91], v[74:75], v[8:9] op_sel_hi:[1,0]
	v_pk_mul_f32 v[88:89], v[72:73], v[8:9] op_sel_hi:[1,0]
	v_pk_mul_f32 v[86:87], v[70:71], v[8:9] op_sel_hi:[1,0]
	v_pk_mul_f32 v[84:85], v[68:69], v[8:9] op_sel_hi:[1,0]
	v_pk_mul_f32 v[82:83], v[66:67], v[8:9] op_sel_hi:[1,0]
	v_pk_add_f32 v[144:145], v[144:145], v[6:7] op_sel_hi:[1,0] neg_lo:[0,1] neg_hi:[0,1]
	v_pk_add_f32 v[128:129], v[128:129], v[6:7] op_sel_hi:[1,0] neg_lo:[0,1] neg_hi:[0,1]
	s_branch .LBB0_413
